# attention K/V staging rewritten: 16 row loads issued up front, DPP row sums for the k-norm, immediate-offset transposed V writes
# baseline (speedup 1.0000x reference)
; __device__ __forceinline__ u32x4 pack8(f32x4 a, f32x4 b) { u32x4 w; w.x = cvt_pk_bf16(a[0], a[1]); w.y = cvt_pk_bf16(a[2], a[3]); w.z = cvt_pk_bf16(b[0], b[1]); w.w = cvt_pk_bf16(b[2], b[3]); return w; }
; #define LAS __attribute__((address_space(3)))
; __device__ __forceinline__ void attn_unit(LAS unsigned char* lds, const bf16_t* PROJ, bf16_t* YCAT, const float* qg, const float* kg, const float* sinks, int unit, int tid, int wave, int lane) {
;     ...
;     {
;         const int c16 = tid & 15;
;         const f32x4 g0 = *(const f32x4*)(kg + 8 * c16), g1 = *(const f32x4*)(kg + 8 * c16 + 4);
; #pragma unroll 2
;         for (int pass = 0; pass < 8; ++pass) {
;             const int kidx = (tid >> 4) + 32 * pass;
;             u32x4 w = {0u, 0u, 0u, 0u};
;             if (!(blk == 0 && pass < 4)) w = *(const u32x4*)(PROJ + (size_t)(t0 - 128 + kidx) * INW + 1024 + kvh * 128 + 8 * c16);
;             f32x4 v0, v1; pg8::unpack8(w, v0, v1);
;             float ss = (v0[0] * v0[0] + v0[1] * v0[1]) + (v0[2] * v0[2] + v0[3] * v0[3]) + (v1[0] * v1[0] + v1[1] * v1[1]) + (v1[2] * v1[2] + v1[3] * v1[3]);
;             ss += __shfl_xor(ss, 1); ss += __shfl_xor(ss, 2); ss += __shfl_xor(ss, 4); ss += __shfl_xor(ss, 8);
;             const float rs = rsqrtf(ss * (1.f / 128.f) + EPS);
;             *(LAS u32x4*)(Ks + kidx * 136 + 8 * c16) = pg8::pack8(v0 * rs * g0, v1 * rs * g1);
;         }
;     }
;     {
; #pragma unroll 1
;         for (int rg = 0; rg < 4; ++rg) {
;             const int kidx = 64 * rg + lane, kk = kidx & 31, pos = (kidx & ~31) + 8 * ((kk >> 2) & 3) + 4 * (kk >> 4) + (kk & 3);
; #pragma unroll
;             for (int cc = 0; cc < 2; ++cc) {
;                 const int c16 = 2 * wave + cc;
;                 u32x4 w = {0u, 0u, 0u, 0u};
;                 if (!(blk == 0 && rg < 2)) w = *(const u32x4*)(PROJ + (size_t)(t0 - 128 + kidx) * INW + 1280 + kvh * 128 + 8 * c16);
;                 LAS bf16_t* d = Vt + (8 * c16) * 264 + pos;
;                 d[0 * 264] = (bf16_t)(w.x & 0xffffu); d[1 * 264] = (bf16_t)(w.x >> 16); d[2 * 264] = (bf16_t)(w.y & 0xffffu); d[3 * 264] = (bf16_t)(w.y >> 16);
;                 d[4 * 264] = (bf16_t)(w.z & 0xffffu); d[5 * 264] = (bf16_t)(w.z >> 16); d[6 * 264] = (bf16_t)(w.w & 0xffffu); d[7 * 264] = (bf16_t)(w.w >> 16);
;             }
;         }
;     }
.LBB0_157:
	s_bfe_u32 s66, s83, 0x60001
	s_and_b32 s10, s82, 0xffffe000
	s_lshl_b32 s13, s66, 7
	s_or_b32 s2, s13, s10
	s_and_b32 s12, s83, 1
	v_add_u32_e32 v0, s2, v142
	s_lshl_b32 s78, s12, 8
	s_lshl_b32 s11, s12, 7
	v_lshl_add_u64 v[170:171], v[82:83], 0, s[78:79]
	s_add_i32 s14, s13, s10
	s_lshl_b32 s8, s11, 1
	s_add_u32 s8, s68, s8
	s_addc_u32 s9, s69, 0
	v_add_u32_e32 v46, s14, v143
	v_mov_b64_e32 v[44:45], s[8:9]
	v_readlane_b32 s20, v254, 6
	v_readlane_b32 s21, v254, 7
	s_lshl_b32 s78, s23, 1
	s_mov_b32 s15, 0x800000
	s_cmp_eq_u32 s66, 0
	s_mov_b32 s21, s79
	s_cbranch_scc1 .Lat_first_blk
	v_mad_i64_i32 v[42:43], s[16:17], v0, s81, v[170:171]
	global_load_dwordx4 v[10:13], v[42:43], off offset:2048
	v_add_u32_e32 v47, 32, v0
	v_mad_i64_i32 v[42:43], s[16:17], v47, s81, v[170:171]
	global_load_dwordx4 v[14:17], v[42:43], off offset:2048
	v_add_u32_e32 v47, 64, v0
	v_mad_i64_i32 v[42:43], s[16:17], v47, s81, v[170:171]
	global_load_dwordx4 v[18:21], v[42:43], off offset:2048
	v_add_u32_e32 v47, 96, v0
	v_mad_i64_i32 v[42:43], s[16:17], v47, s81, v[170:171]
	global_load_dwordx4 v[22:25], v[42:43], off offset:2048
	v_mad_i64_i32 v[42:43], s[18:19], v46, s81, v[44:45]
	v_lshl_add_u64 v[48:49], v[42:43], 0, s[78:79]
	global_load_dwordx4 v[208:211], v[48:49], off offset:2560
	v_lshl_add_u64 v[48:49], v[42:43], 0, s[20:21]
	global_load_dwordx4 v[212:215], v[48:49], off offset:2560
	v_add_u32_e32 v47, 64, v46
	v_mad_i64_i32 v[42:43], s[18:19], v47, s81, v[44:45]
	v_lshl_add_u64 v[48:49], v[42:43], 0, s[78:79]
	global_load_dwordx4 v[216:219], v[48:49], off offset:2560
	v_lshl_add_u64 v[48:49], v[42:43], 0, s[20:21]
	global_load_dwordx4 v[220:223], v[48:49], off offset:2560
	s_branch .Lat_rest
.Lat_first_blk:
	v_mov_b32_e32 v10, 0
	v_mov_b32_e32 v11, 0
	v_mov_b32_e32 v12, 0
	v_mov_b32_e32 v13, 0
	v_mov_b32_e32 v14, 0
	v_mov_b32_e32 v15, 0
	v_mov_b32_e32 v16, 0
	v_mov_b32_e32 v17, 0
	v_mov_b32_e32 v18, 0
	v_mov_b32_e32 v19, 0
	v_mov_b32_e32 v20, 0
	v_mov_b32_e32 v21, 0
	v_mov_b32_e32 v22, 0
	v_mov_b32_e32 v23, 0
	v_mov_b32_e32 v24, 0
	v_mov_b32_e32 v25, 0
	v_mov_b32_e32 v208, 0
	v_mov_b32_e32 v209, 0
	v_mov_b32_e32 v210, 0
	v_mov_b32_e32 v211, 0
	v_mov_b32_e32 v212, 0
	v_mov_b32_e32 v213, 0
	v_mov_b32_e32 v214, 0
	v_mov_b32_e32 v215, 0
	v_mov_b32_e32 v216, 0
	v_mov_b32_e32 v217, 0
	v_mov_b32_e32 v218, 0
	v_mov_b32_e32 v219, 0
	v_mov_b32_e32 v220, 0
	v_mov_b32_e32 v221, 0
	v_mov_b32_e32 v222, 0
	v_mov_b32_e32 v223, 0
.Lat_rest:
	global_load_dwordx4 v[2:5], v[78:79], off offset:16
	global_load_dwordx4 v[6:9], v[78:79], off
	v_add_u32_e32 v47, 128, v0
	v_mad_i64_i32 v[42:43], s[16:17], v47, s81, v[170:171]
	global_load_dwordx4 v[26:29], v[42:43], off offset:2048
	v_add_u32_e32 v47, 160, v0
	v_mad_i64_i32 v[42:43], s[16:17], v47, s81, v[170:171]
	global_load_dwordx4 v[30:33], v[42:43], off offset:2048
	v_add_u32_e32 v47, 192, v0
	v_mad_i64_i32 v[42:43], s[16:17], v47, s81, v[170:171]
	global_load_dwordx4 v[34:37], v[42:43], off offset:2048
	v_add_u32_e32 v47, 224, v0
	v_mad_i64_i32 v[42:43], s[16:17], v47, s81, v[170:171]
	global_load_dwordx4 v[38:41], v[42:43], off offset:2048
	v_add_u32_e32 v47, 128, v46
	v_mad_i64_i32 v[42:43], s[18:19], v47, s81, v[44:45]
	v_lshl_add_u64 v[48:49], v[42:43], 0, s[78:79]
	global_load_dwordx4 v[224:227], v[48:49], off offset:2560
	v_lshl_add_u64 v[48:49], v[42:43], 0, s[20:21]
	global_load_dwordx4 v[228:231], v[48:49], off offset:2560
	v_add_u32_e32 v47, 192, v46
	v_mad_i64_i32 v[42:43], s[18:19], v47, s81, v[44:45]
	v_lshl_add_u64 v[48:49], v[42:43], 0, s[78:79]
	global_load_dwordx4 v[232:235], v[48:49], off offset:2560
	v_lshl_add_u64 v[48:49], v[42:43], 0, s[20:21]
	global_load_dwordx4 v[236:239], v[48:49], off offset:2560
	s_waitcnt vmcnt(8)
	v_and_b32_e32 v49, 0xffff0000, v10
	v_lshlrev_b32_e32 v48, 16, v10
	v_and_b32_e32 v61, 0xffff0000, v14
	v_lshlrev_b32_e32 v60, 16, v14
	v_and_b32_e32 v51, 0xffff0000, v11
	v_lshlrev_b32_e32 v50, 16, v11
	v_and_b32_e32 v63, 0xffff0000, v15
	v_lshlrev_b32_e32 v62, 16, v15
	v_and_b32_e32 v53, 0xffff0000, v12
	v_lshlrev_b32_e32 v52, 16, v12
	v_and_b32_e32 v65, 0xffff0000, v16
	v_lshlrev_b32_e32 v64, 16, v16
	v_and_b32_e32 v55, 0xffff0000, v13
	v_lshlrev_b32_e32 v54, 16, v13
	v_and_b32_e32 v67, 0xffff0000, v17
	v_lshlrev_b32_e32 v66, 16, v17
	v_pk_mul_f32 v[56:57], v[48:49], v[48:49]
	v_pk_mul_f32 v[68:69], v[60:61], v[60:61]
	v_pk_fma_f32 v[56:57], v[50:51], v[50:51], v[56:57]
	v_pk_fma_f32 v[68:69], v[62:63], v[62:63], v[68:69]
	v_pk_fma_f32 v[56:57], v[52:53], v[52:53], v[56:57]
	v_pk_fma_f32 v[68:69], v[64:65], v[64:65], v[68:69]
	v_pk_fma_f32 v[56:57], v[54:55], v[54:55], v[56:57]
	v_pk_fma_f32 v[68:69], v[66:67], v[66:67], v[68:69]
	v_add_f32_e32 v58, v56, v57
	v_add_f32_e32 v87, v68, v69
	s_nop 0
	v_add_f32_dpp v58, v58, v58 quad_perm:[1,0,3,2] row_mask:0xf bank_mask:0xf
	v_add_f32_dpp v87, v87, v87 quad_perm:[1,0,3,2] row_mask:0xf bank_mask:0xf
	s_nop 0
	v_add_f32_dpp v58, v58, v58 quad_perm:[2,3,0,1] row_mask:0xf bank_mask:0xf
	v_add_f32_dpp v87, v87, v87 quad_perm:[2,3,0,1] row_mask:0xf bank_mask:0xf
	s_nop 0
	v_add_f32_dpp v58, v58, v58 row_half_mirror row_mask:0xf bank_mask:0xf
	v_add_f32_dpp v87, v87, v87 row_half_mirror row_mask:0xf bank_mask:0xf
	s_nop 0
	v_add_f32_dpp v58, v58, v58 row_mirror row_mask:0xf bank_mask:0xf
	v_add_f32_dpp v87, v87, v87 row_mirror row_mask:0xf bank_mask:0xf
	s_nop 0
	v_fmamk_f32 v58, v58, 0x3c000000, v197
	v_fmamk_f32 v87, v87, 0x3c000000, v197
	v_mul_f32_e32 v59, 0x4b800000, v58
	v_mul_f32_e32 v88, 0x4b800000, v87
	v_cmp_gt_f32_e64 s[8:9], s15, v58
	v_cmp_gt_f32_e64 s[10:11], s15, v87
	s_nop 0
	v_cndmask_b32_e64 v58, v58, v59, s[8:9]
; __device__ __forceinline__ u32x4 pack8(f32x4 a, f32x4 b) { u32x4 w; w.x = cvt_pk_bf16(a[0], a[1]); w.y = cvt_pk_bf16(a[2], a[3]); w.z = cvt_pk_bf16(b[0], b[1]); w.w = cvt_pk_bf16(b[2], b[3]); return w; }
; __device__ __forceinline__ void unpack8(u32x4 w, f32x4& a, f32x4& b) { a = (f32x4){bf_lo(w.x), bf_hi(w.x), bf_lo(w.y), bf_hi(w.y)}; b = (f32x4){bf_lo(w.z), bf_hi(w.z), bf_lo(w.w), bf_hi(w.w)}; }
; #define LAS __attribute__((address_space(3)))
; __device__ __forceinline__ void attn_unit(LAS unsigned char* lds, const bf16_t* PROJ, bf16_t* YCAT, const float* qg, const float* kg, const float* sinks, int unit, int tid, int wave, int lane) {
;     ...
;         const int c16 = tid & 15;
;         const f32x4 g0 = *(const f32x4*)(kg + 8 * c16), g1 = *(const f32x4*)(kg + 8 * c16 + 4);
; #pragma unroll 2
;         for (int pass = 0; pass < 8; ++pass) {
;             const int kidx = (tid >> 4) + 32 * pass;
;             u32x4 w = {0u, 0u, 0u, 0u};
;             if (!(blk == 0 && pass < 4)) w = *(const u32x4*)(PROJ + (size_t)(t0 - 128 + kidx) * INW + 1024 + kvh * 128 + 8 * c16);
;             f32x4 v0, v1; pg8::unpack8(w, v0, v1);
;             float ss = (v0[0] * v0[0] + v0[1] * v0[1]) + (v0[2] * v0[2] + v0[3] * v0[3]) + (v1[0] * v1[0] + v1[1] * v1[1]) + (v1[2] * v1[2] + v1[3] * v1[3]);
;             ss += __shfl_xor(ss, 1); ss += __shfl_xor(ss, 2); ss += __shfl_xor(ss, 4); ss += __shfl_xor(ss, 8);
;             const float rs = rsqrtf(ss * (1.f / 128.f) + EPS);
;             *(LAS u32x4*)(Ks + kidx * 136 + 8 * c16) = pg8::pack8(v0 * rs * g0, v1 * rs * g1);
;         }
	v_cndmask_b32_e64 v87, v87, v88, s[10:11]
	v_rsq_f32_e32 v58, v58
	v_rsq_f32_e32 v87, v87
	v_mul_f32_e32 v59, 0x45800000, v58
	v_mul_f32_e32 v88, 0x45800000, v87
	v_cndmask_b32_e64 v90, v58, v59, s[8:9]
	v_cndmask_b32_e64 v92, v87, v88, s[10:11]
	v_pk_mul_f32 v[48:49], v[48:49], v[90:91] op_sel_hi:[1,0]
	v_pk_mul_f32 v[60:61], v[60:61], v[92:93] op_sel_hi:[1,0]
	v_pk_mul_f32 v[50:51], v[50:51], v[90:91] op_sel_hi:[1,0]
	v_pk_mul_f32 v[62:63], v[62:63], v[92:93] op_sel_hi:[1,0]
	v_pk_mul_f32 v[52:53], v[52:53], v[90:91] op_sel_hi:[1,0]
	v_pk_mul_f32 v[64:65], v[64:65], v[92:93] op_sel_hi:[1,0]
	v_pk_mul_f32 v[54:55], v[54:55], v[90:91] op_sel_hi:[1,0]
	v_pk_mul_f32 v[66:67], v[66:67], v[92:93] op_sel_hi:[1,0]
	v_pk_mul_f32 v[48:49], v[6:7], v[48:49]
	v_pk_mul_f32 v[60:61], v[6:7], v[60:61]
	v_pk_mul_f32 v[50:51], v[8:9], v[50:51]
	v_pk_mul_f32 v[62:63], v[8:9], v[62:63]
	v_pk_mul_f32 v[52:53], v[2:3], v[52:53]
	v_pk_mul_f32 v[64:65], v[2:3], v[64:65]
	v_pk_mul_f32 v[54:55], v[4:5], v[54:55]
	v_pk_mul_f32 v[66:67], v[4:5], v[66:67]
	v_cvt_pk_bf16_f32 v48, v48, v49
	v_cvt_pk_bf16_f32 v60, v60, v61
	v_cvt_pk_bf16_f32 v49, v50, v51
	v_cvt_pk_bf16_f32 v61, v62, v63
	v_cvt_pk_bf16_f32 v50, v52, v53
	v_cvt_pk_bf16_f32 v62, v64, v65
	v_cvt_pk_bf16_f32 v51, v54, v55
	v_cvt_pk_bf16_f32 v63, v66, v67
	ds_write_b128 v141, v[48:51]
	ds_write_b128 v141, v[60:63] offset:8704
	v_and_b32_e32 v49, 0xffff0000, v18
	v_lshlrev_b32_e32 v48, 16, v18
	v_and_b32_e32 v61, 0xffff0000, v22
	v_lshlrev_b32_e32 v60, 16, v22
	v_and_b32_e32 v51, 0xffff0000, v19
	v_lshlrev_b32_e32 v50, 16, v19
	v_and_b32_e32 v63, 0xffff0000, v23
	v_lshlrev_b32_e32 v62, 16, v23
	v_and_b32_e32 v53, 0xffff0000, v20
	v_lshlrev_b32_e32 v52, 16, v20
	v_and_b32_e32 v65, 0xffff0000, v24
	v_lshlrev_b32_e32 v64, 16, v24
	v_and_b32_e32 v55, 0xffff0000, v21
	v_lshlrev_b32_e32 v54, 16, v21
	v_and_b32_e32 v67, 0xffff0000, v25
	v_lshlrev_b32_e32 v66, 16, v25
	v_pk_mul_f32 v[56:57], v[48:49], v[48:49]
	v_pk_mul_f32 v[68:69], v[60:61], v[60:61]
	v_pk_fma_f32 v[56:57], v[50:51], v[50:51], v[56:57]
	v_pk_fma_f32 v[68:69], v[62:63], v[62:63], v[68:69]
	v_pk_fma_f32 v[56:57], v[52:53], v[52:53], v[56:57]
	v_pk_fma_f32 v[68:69], v[64:65], v[64:65], v[68:69]
	v_pk_fma_f32 v[56:57], v[54:55], v[54:55], v[56:57]
	v_pk_fma_f32 v[68:69], v[66:67], v[66:67], v[68:69]
	v_add_f32_e32 v58, v56, v57
	v_add_f32_e32 v87, v68, v69
	s_nop 0
	v_add_f32_dpp v58, v58, v58 quad_perm:[1,0,3,2] row_mask:0xf bank_mask:0xf
	v_add_f32_dpp v87, v87, v87 quad_perm:[1,0,3,2] row_mask:0xf bank_mask:0xf
	s_nop 0
	v_add_f32_dpp v58, v58, v58 quad_perm:[2,3,0,1] row_mask:0xf bank_mask:0xf
	v_add_f32_dpp v87, v87, v87 quad_perm:[2,3,0,1] row_mask:0xf bank_mask:0xf
	s_nop 0
	v_add_f32_dpp v58, v58, v58 row_half_mirror row_mask:0xf bank_mask:0xf
	v_add_f32_dpp v87, v87, v87 row_half_mirror row_mask:0xf bank_mask:0xf
	s_nop 0
	v_add_f32_dpp v58, v58, v58 row_mirror row_mask:0xf bank_mask:0xf
	v_add_f32_dpp v87, v87, v87 row_mirror row_mask:0xf bank_mask:0xf
	s_nop 0
	v_fmamk_f32 v58, v58, 0x3c000000, v197
	v_fmamk_f32 v87, v87, 0x3c000000, v197
	v_mul_f32_e32 v59, 0x4b800000, v58
	v_mul_f32_e32 v88, 0x4b800000, v87
	v_cmp_gt_f32_e64 s[8:9], s15, v58
	v_cmp_gt_f32_e64 s[10:11], s15, v87
	s_nop 0
	v_cndmask_b32_e64 v58, v58, v59, s[8:9]
	v_cndmask_b32_e64 v87, v87, v88, s[10:11]
	v_rsq_f32_e32 v58, v58
	v_rsq_f32_e32 v87, v87
	v_mul_f32_e32 v59, 0x45800000, v58
	v_mul_f32_e32 v88, 0x45800000, v87
	v_cndmask_b32_e64 v90, v58, v59, s[8:9]
	v_cndmask_b32_e64 v92, v87, v88, s[10:11]
	v_pk_mul_f32 v[48:49], v[48:49], v[90:91] op_sel_hi:[1,0]
	v_pk_mul_f32 v[60:61], v[60:61], v[92:93] op_sel_hi:[1,0]
	v_pk_mul_f32 v[50:51], v[50:51], v[90:91] op_sel_hi:[1,0]
	v_pk_mul_f32 v[62:63], v[62:63], v[92:93] op_sel_hi:[1,0]
	v_pk_mul_f32 v[52:53], v[52:53], v[90:91] op_sel_hi:[1,0]
	v_pk_mul_f32 v[64:65], v[64:65], v[92:93] op_sel_hi:[1,0]
	v_pk_mul_f32 v[54:55], v[54:55], v[90:91] op_sel_hi:[1,0]
	v_pk_mul_f32 v[66:67], v[66:67], v[92:93] op_sel_hi:[1,0]
	v_pk_mul_f32 v[48:49], v[6:7], v[48:49]
	v_pk_mul_f32 v[60:61], v[6:7], v[60:61]
	v_pk_mul_f32 v[50:51], v[8:9], v[50:51]
	v_pk_mul_f32 v[62:63], v[8:9], v[62:63]
	v_pk_mul_f32 v[52:53], v[2:3], v[52:53]
	v_pk_mul_f32 v[64:65], v[2:3], v[64:65]
	v_pk_mul_f32 v[54:55], v[4:5], v[54:55]
	v_pk_mul_f32 v[66:67], v[4:5], v[66:67]
	v_cvt_pk_bf16_f32 v48, v48, v49
	v_cvt_pk_bf16_f32 v60, v60, v61
	v_cvt_pk_bf16_f32 v49, v50, v51
	v_cvt_pk_bf16_f32 v61, v62, v63
	v_cvt_pk_bf16_f32 v50, v52, v53
	v_cvt_pk_bf16_f32 v62, v64, v65
	v_cvt_pk_bf16_f32 v51, v54, v55
	v_cvt_pk_bf16_f32 v63, v66, v67
	ds_write_b128 v141, v[48:51] offset:17408
	ds_write_b128 v141, v[60:63] offset:26112
	s_waitcnt vmcnt(4)
; __device__ __forceinline__ u32x4 pack8(f32x4 a, f32x4 b) { u32x4 w; w.x = cvt_pk_bf16(a[0], a[1]); w.y = cvt_pk_bf16(a[2], a[3]); w.z = cvt_pk_bf16(b[0], b[1]); w.w = cvt_pk_bf16(b[2], b[3]); return w; }
; __device__ __forceinline__ void unpack8(u32x4 w, f32x4& a, f32x4& b) { a = (f32x4){bf_lo(w.x), bf_hi(w.x), bf_lo(w.y), bf_hi(w.y)}; b = (f32x4){bf_lo(w.z), bf_hi(w.z), bf_lo(w.w), bf_hi(w.w)}; }
; #define LAS __attribute__((address_space(3)))
; __device__ __forceinline__ void attn_unit(LAS unsigned char* lds, const bf16_t* PROJ, bf16_t* YCAT, const float* qg, const float* kg, const float* sinks, int unit, int tid, int wave, int lane) {
;     ...
;         const int c16 = tid & 15;
;         const f32x4 g0 = *(const f32x4*)(kg + 8 * c16), g1 = *(const f32x4*)(kg + 8 * c16 + 4);
; #pragma unroll 2
;         for (int pass = 0; pass < 8; ++pass) {
;             const int kidx = (tid >> 4) + 32 * pass;
;             u32x4 w = {0u, 0u, 0u, 0u};
;             if (!(blk == 0 && pass < 4)) w = *(const u32x4*)(PROJ + (size_t)(t0 - 128 + kidx) * INW + 1024 + kvh * 128 + 8 * c16);
;             f32x4 v0, v1; pg8::unpack8(w, v0, v1);
;             float ss = (v0[0] * v0[0] + v0[1] * v0[1]) + (v0[2] * v0[2] + v0[3] * v0[3]) + (v1[0] * v1[0] + v1[1] * v1[1]) + (v1[2] * v1[2] + v1[3] * v1[3]);
;             ss += __shfl_xor(ss, 1); ss += __shfl_xor(ss, 2); ss += __shfl_xor(ss, 4); ss += __shfl_xor(ss, 8);
;             const float rs = rsqrtf(ss * (1.f / 128.f) + EPS);
;             *(LAS u32x4*)(Ks + kidx * 136 + 8 * c16) = pg8::pack8(v0 * rs * g0, v1 * rs * g1);
;         }
	v_and_b32_e32 v49, 0xffff0000, v26
	v_lshlrev_b32_e32 v48, 16, v26
	v_and_b32_e32 v61, 0xffff0000, v30
	v_lshlrev_b32_e32 v60, 16, v30
	v_and_b32_e32 v51, 0xffff0000, v27
	v_lshlrev_b32_e32 v50, 16, v27
	v_and_b32_e32 v63, 0xffff0000, v31
	v_lshlrev_b32_e32 v62, 16, v31
	v_and_b32_e32 v53, 0xffff0000, v28
	v_lshlrev_b32_e32 v52, 16, v28
	v_and_b32_e32 v65, 0xffff0000, v32
	v_lshlrev_b32_e32 v64, 16, v32
	v_and_b32_e32 v55, 0xffff0000, v29
	v_lshlrev_b32_e32 v54, 16, v29
	v_and_b32_e32 v67, 0xffff0000, v33
	v_lshlrev_b32_e32 v66, 16, v33
	v_pk_mul_f32 v[56:57], v[48:49], v[48:49]
	v_pk_mul_f32 v[68:69], v[60:61], v[60:61]
	v_pk_fma_f32 v[56:57], v[50:51], v[50:51], v[56:57]
	v_pk_fma_f32 v[68:69], v[62:63], v[62:63], v[68:69]
	v_pk_fma_f32 v[56:57], v[52:53], v[52:53], v[56:57]
	v_pk_fma_f32 v[68:69], v[64:65], v[64:65], v[68:69]
	v_pk_fma_f32 v[56:57], v[54:55], v[54:55], v[56:57]
	v_pk_fma_f32 v[68:69], v[66:67], v[66:67], v[68:69]
	v_add_f32_e32 v58, v56, v57
	v_add_f32_e32 v87, v68, v69
	s_nop 0
	v_add_f32_dpp v58, v58, v58 quad_perm:[1,0,3,2] row_mask:0xf bank_mask:0xf
	v_add_f32_dpp v87, v87, v87 quad_perm:[1,0,3,2] row_mask:0xf bank_mask:0xf
	s_nop 0
	v_add_f32_dpp v58, v58, v58 quad_perm:[2,3,0,1] row_mask:0xf bank_mask:0xf
	v_add_f32_dpp v87, v87, v87 quad_perm:[2,3,0,1] row_mask:0xf bank_mask:0xf
	s_nop 0
	v_add_f32_dpp v58, v58, v58 row_half_mirror row_mask:0xf bank_mask:0xf
	v_add_f32_dpp v87, v87, v87 row_half_mirror row_mask:0xf bank_mask:0xf
	s_nop 0
	v_add_f32_dpp v58, v58, v58 row_mirror row_mask:0xf bank_mask:0xf
	v_add_f32_dpp v87, v87, v87 row_mirror row_mask:0xf bank_mask:0xf
	s_nop 0
	v_fmamk_f32 v58, v58, 0x3c000000, v197
	v_fmamk_f32 v87, v87, 0x3c000000, v197
	v_mul_f32_e32 v59, 0x4b800000, v58
	v_mul_f32_e32 v88, 0x4b800000, v87
	v_cmp_gt_f32_e64 s[8:9], s15, v58
	v_cmp_gt_f32_e64 s[10:11], s15, v87
	s_nop 0
	v_cndmask_b32_e64 v58, v58, v59, s[8:9]
	v_cndmask_b32_e64 v87, v87, v88, s[10:11]
	v_rsq_f32_e32 v58, v58
	v_rsq_f32_e32 v87, v87
	v_mul_f32_e32 v59, 0x45800000, v58
	v_mul_f32_e32 v88, 0x45800000, v87
	v_cndmask_b32_e64 v90, v58, v59, s[8:9]
	v_cndmask_b32_e64 v92, v87, v88, s[10:11]
	v_pk_mul_f32 v[48:49], v[48:49], v[90:91] op_sel_hi:[1,0]
	v_pk_mul_f32 v[60:61], v[60:61], v[92:93] op_sel_hi:[1,0]
	v_pk_mul_f32 v[50:51], v[50:51], v[90:91] op_sel_hi:[1,0]
	v_pk_mul_f32 v[62:63], v[62:63], v[92:93] op_sel_hi:[1,0]
	v_pk_mul_f32 v[52:53], v[52:53], v[90:91] op_sel_hi:[1,0]
	v_pk_mul_f32 v[64:65], v[64:65], v[92:93] op_sel_hi:[1,0]
	v_pk_mul_f32 v[54:55], v[54:55], v[90:91] op_sel_hi:[1,0]
	v_pk_mul_f32 v[66:67], v[66:67], v[92:93] op_sel_hi:[1,0]
	v_pk_mul_f32 v[48:49], v[6:7], v[48:49]
	v_pk_mul_f32 v[60:61], v[6:7], v[60:61]
	v_pk_mul_f32 v[50:51], v[8:9], v[50:51]
	v_pk_mul_f32 v[62:63], v[8:9], v[62:63]
	v_pk_mul_f32 v[52:53], v[2:3], v[52:53]
	v_pk_mul_f32 v[64:65], v[2:3], v[64:65]
	v_pk_mul_f32 v[54:55], v[4:5], v[54:55]
	v_pk_mul_f32 v[66:67], v[4:5], v[66:67]
	v_cvt_pk_bf16_f32 v48, v48, v49
	v_cvt_pk_bf16_f32 v60, v60, v61
	v_cvt_pk_bf16_f32 v49, v50, v51
	v_cvt_pk_bf16_f32 v61, v62, v63
	v_cvt_pk_bf16_f32 v50, v52, v53
	v_cvt_pk_bf16_f32 v62, v64, v65
	v_cvt_pk_bf16_f32 v51, v54, v55
	v_cvt_pk_bf16_f32 v63, v66, v67
	ds_write_b128 v141, v[48:51] offset:34816
	ds_write_b128 v141, v[60:63] offset:43520
	v_and_b32_e32 v49, 0xffff0000, v34
	v_lshlrev_b32_e32 v48, 16, v34
	v_and_b32_e32 v61, 0xffff0000, v38
	v_lshlrev_b32_e32 v60, 16, v38
	v_and_b32_e32 v51, 0xffff0000, v35
	v_lshlrev_b32_e32 v50, 16, v35
	v_and_b32_e32 v63, 0xffff0000, v39
	v_lshlrev_b32_e32 v62, 16, v39
	v_and_b32_e32 v53, 0xffff0000, v36
	v_lshlrev_b32_e32 v52, 16, v36
	v_and_b32_e32 v65, 0xffff0000, v40
	v_lshlrev_b32_e32 v64, 16, v40
	v_and_b32_e32 v55, 0xffff0000, v37
	v_lshlrev_b32_e32 v54, 16, v37
	v_and_b32_e32 v67, 0xffff0000, v41
	v_lshlrev_b32_e32 v66, 16, v41
	v_pk_mul_f32 v[56:57], v[48:49], v[48:49]
	v_pk_mul_f32 v[68:69], v[60:61], v[60:61]
	v_pk_fma_f32 v[56:57], v[50:51], v[50:51], v[56:57]
	v_pk_fma_f32 v[68:69], v[62:63], v[62:63], v[68:69]
	v_pk_fma_f32 v[56:57], v[52:53], v[52:53], v[56:57]
	v_pk_fma_f32 v[68:69], v[64:65], v[64:65], v[68:69]
	v_pk_fma_f32 v[56:57], v[54:55], v[54:55], v[56:57]
	v_pk_fma_f32 v[68:69], v[66:67], v[66:67], v[68:69]
	v_add_f32_e32 v58, v56, v57
	v_add_f32_e32 v87, v68, v69
	s_nop 0
	v_add_f32_dpp v58, v58, v58 quad_perm:[1,0,3,2] row_mask:0xf bank_mask:0xf
	v_add_f32_dpp v87, v87, v87 quad_perm:[1,0,3,2] row_mask:0xf bank_mask:0xf
	s_nop 0
	v_add_f32_dpp v58, v58, v58 quad_perm:[2,3,0,1] row_mask:0xf bank_mask:0xf
	v_add_f32_dpp v87, v87, v87 quad_perm:[2,3,0,1] row_mask:0xf bank_mask:0xf
; __device__ __forceinline__ u32x4 pack8(f32x4 a, f32x4 b) { u32x4 w; w.x = cvt_pk_bf16(a[0], a[1]); w.y = cvt_pk_bf16(a[2], a[3]); w.z = cvt_pk_bf16(b[0], b[1]); w.w = cvt_pk_bf16(b[2], b[3]); return w; }
; __device__ __forceinline__ void unpack8(u32x4 w, f32x4& a, f32x4& b) { a = (f32x4){bf_lo(w.x), bf_hi(w.x), bf_lo(w.y), bf_hi(w.y)}; b = (f32x4){bf_lo(w.z), bf_hi(w.z), bf_lo(w.w), bf_hi(w.w)}; }
; #define LAS __attribute__((address_space(3)))
; __device__ __forceinline__ void attn_unit(LAS unsigned char* lds, const bf16_t* PROJ, bf16_t* YCAT, const float* qg, const float* kg, const float* sinks, int unit, int tid, int wave, int lane) {
;     ...
;             f32x4 v0, v1; pg8::unpack8(w, v0, v1);
;             float ss = (v0[0] * v0[0] + v0[1] * v0[1]) + (v0[2] * v0[2] + v0[3] * v0[3]) + (v1[0] * v1[0] + v1[1] * v1[1]) + (v1[2] * v1[2] + v1[3] * v1[3]);
;             ss += __shfl_xor(ss, 1); ss += __shfl_xor(ss, 2); ss += __shfl_xor(ss, 4); ss += __shfl_xor(ss, 8);
;             const float rs = rsqrtf(ss * (1.f / 128.f) + EPS);
;             *(LAS u32x4*)(Ks + kidx * 136 + 8 * c16) = pg8::pack8(v0 * rs * g0, v1 * rs * g1);
;         }
;     }
;     {
; #pragma unroll 1
;         for (int rg = 0; rg < 4; ++rg) {
;             const int kidx = 64 * rg + lane, kk = kidx & 31, pos = (kidx & ~31) + 8 * ((kk >> 2) & 3) + 4 * (kk >> 4) + (kk & 3);
; #pragma unroll
;             for (int cc = 0; cc < 2; ++cc) {
;                 const int c16 = 2 * wave + cc;
;                 u32x4 w = {0u, 0u, 0u, 0u};
;                 if (!(blk == 0 && rg < 2)) w = *(const u32x4*)(PROJ + (size_t)(t0 - 128 + kidx) * INW + 1280 + kvh * 128 + 8 * c16);
;                 LAS bf16_t* d = Vt + (8 * c16) * 264 + pos;
;                 d[0 * 264] = (bf16_t)(w.x & 0xffffu); d[1 * 264] = (bf16_t)(w.x >> 16); d[2 * 264] = (bf16_t)(w.y & 0xffffu); d[3 * 264] = (bf16_t)(w.y >> 16);
;                 d[4 * 264] = (bf16_t)(w.z & 0xffffu); d[5 * 264] = (bf16_t)(w.z >> 16); d[6 * 264] = (bf16_t)(w.w & 0xffffu); d[7 * 264] = (bf16_t)(w.w >> 16);
;             }
;         }
	s_nop 0
	v_add_f32_dpp v58, v58, v58 row_half_mirror row_mask:0xf bank_mask:0xf
	v_add_f32_dpp v87, v87, v87 row_half_mirror row_mask:0xf bank_mask:0xf
	s_nop 0
	v_add_f32_dpp v58, v58, v58 row_mirror row_mask:0xf bank_mask:0xf
	v_add_f32_dpp v87, v87, v87 row_mirror row_mask:0xf bank_mask:0xf
	s_nop 0
	v_fmamk_f32 v58, v58, 0x3c000000, v197
	v_fmamk_f32 v87, v87, 0x3c000000, v197
	v_mul_f32_e32 v59, 0x4b800000, v58
	v_mul_f32_e32 v88, 0x4b800000, v87
	v_cmp_gt_f32_e64 s[8:9], s15, v58
	v_cmp_gt_f32_e64 s[10:11], s15, v87
	s_nop 0
	v_cndmask_b32_e64 v58, v58, v59, s[8:9]
	v_cndmask_b32_e64 v87, v87, v88, s[10:11]
	v_rsq_f32_e32 v58, v58
	v_rsq_f32_e32 v87, v87
	v_mul_f32_e32 v59, 0x45800000, v58
	v_mul_f32_e32 v88, 0x45800000, v87
	v_cndmask_b32_e64 v90, v58, v59, s[8:9]
	v_cndmask_b32_e64 v92, v87, v88, s[10:11]
	v_pk_mul_f32 v[48:49], v[48:49], v[90:91] op_sel_hi:[1,0]
	v_pk_mul_f32 v[60:61], v[60:61], v[92:93] op_sel_hi:[1,0]
	v_pk_mul_f32 v[50:51], v[50:51], v[90:91] op_sel_hi:[1,0]
	v_pk_mul_f32 v[62:63], v[62:63], v[92:93] op_sel_hi:[1,0]
	v_pk_mul_f32 v[52:53], v[52:53], v[90:91] op_sel_hi:[1,0]
	v_pk_mul_f32 v[64:65], v[64:65], v[92:93] op_sel_hi:[1,0]
	v_pk_mul_f32 v[54:55], v[54:55], v[90:91] op_sel_hi:[1,0]
	v_pk_mul_f32 v[66:67], v[66:67], v[92:93] op_sel_hi:[1,0]
	v_pk_mul_f32 v[48:49], v[6:7], v[48:49]
	v_pk_mul_f32 v[60:61], v[6:7], v[60:61]
	v_pk_mul_f32 v[50:51], v[8:9], v[50:51]
	v_pk_mul_f32 v[62:63], v[8:9], v[62:63]
	v_pk_mul_f32 v[52:53], v[2:3], v[52:53]
	v_pk_mul_f32 v[64:65], v[2:3], v[64:65]
	v_pk_mul_f32 v[54:55], v[4:5], v[54:55]
	v_pk_mul_f32 v[66:67], v[4:5], v[66:67]
	v_cvt_pk_bf16_f32 v48, v48, v49
	v_cvt_pk_bf16_f32 v60, v60, v61
	v_cvt_pk_bf16_f32 v49, v50, v51
	v_cvt_pk_bf16_f32 v61, v62, v63
	v_cvt_pk_bf16_f32 v50, v52, v53
	v_cvt_pk_bf16_f32 v62, v64, v65
	v_cvt_pk_bf16_f32 v51, v54, v55
	v_cvt_pk_bf16_f32 v63, v66, v67
	ds_write_b128 v141, v[48:51] offset:52224
	ds_write_b128 v141, v[60:63] offset:60928
	v_add_u32_e32 v46, 0x11000, v144
	ds_write_b16 v46, v208
	ds_write_b16_d16_hi v46, v208 offset:528
	ds_write_b16 v46, v209 offset:1056
	ds_write_b16_d16_hi v46, v209 offset:1584
	ds_write_b16 v46, v210 offset:2112
	ds_write_b16_d16_hi v46, v210 offset:2640
	ds_write_b16 v46, v211 offset:3168
	ds_write_b16_d16_hi v46, v211 offset:3696
	ds_write_b16 v46, v212 offset:4224
	ds_write_b16_d16_hi v46, v212 offset:4752
	ds_write_b16 v46, v213 offset:5280
	ds_write_b16_d16_hi v46, v213 offset:5808
	ds_write_b16 v46, v214 offset:6336
	ds_write_b16_d16_hi v46, v214 offset:6864
	ds_write_b16 v46, v215 offset:7392
	ds_write_b16_d16_hi v46, v215 offset:7920
	v_add_u32_e32 v46, 0x11080, v144
	ds_write_b16 v46, v216
	ds_write_b16_d16_hi v46, v216 offset:528
	ds_write_b16 v46, v217 offset:1056
	ds_write_b16_d16_hi v46, v217 offset:1584
	ds_write_b16 v46, v218 offset:2112
	ds_write_b16_d16_hi v46, v218 offset:2640
	ds_write_b16 v46, v219 offset:3168
	ds_write_b16_d16_hi v46, v219 offset:3696
	ds_write_b16 v46, v220 offset:4224
	ds_write_b16_d16_hi v46, v220 offset:4752
	ds_write_b16 v46, v221 offset:5280
	ds_write_b16_d16_hi v46, v221 offset:5808
	ds_write_b16 v46, v222 offset:6336
	ds_write_b16_d16_hi v46, v222 offset:6864
	ds_write_b16 v46, v223 offset:7392
	ds_write_b16_d16_hi v46, v223 offset:7920
	s_waitcnt vmcnt(0)
	v_add_u32_e32 v46, 0x11100, v144
	ds_write_b16 v46, v224
	ds_write_b16_d16_hi v46, v224 offset:528
	ds_write_b16 v46, v225 offset:1056
	ds_write_b16_d16_hi v46, v225 offset:1584
	ds_write_b16 v46, v226 offset:2112
	ds_write_b16_d16_hi v46, v226 offset:2640
	ds_write_b16 v46, v227 offset:3168
	ds_write_b16_d16_hi v46, v227 offset:3696
	ds_write_b16 v46, v228 offset:4224
	ds_write_b16_d16_hi v46, v228 offset:4752
	ds_write_b16 v46, v229 offset:5280
	ds_write_b16_d16_hi v46, v229 offset:5808
	ds_write_b16 v46, v230 offset:6336
	ds_write_b16_d16_hi v46, v230 offset:6864
	ds_write_b16 v46, v231 offset:7392
	ds_write_b16_d16_hi v46, v231 offset:7920
	v_add_u32_e32 v46, 0x11180, v144
	ds_write_b16 v46, v232
	ds_write_b16_d16_hi v46, v232 offset:528
	ds_write_b16 v46, v233 offset:1056
	ds_write_b16_d16_hi v46, v233 offset:1584
	ds_write_b16 v46, v234 offset:2112
	ds_write_b16_d16_hi v46, v234 offset:2640
	ds_write_b16 v46, v235 offset:3168
	ds_write_b16_d16_hi v46, v235 offset:3696
	ds_write_b16 v46, v236 offset:4224
	ds_write_b16_d16_hi v46, v236 offset:4752
	ds_write_b16 v46, v237 offset:5280
	ds_write_b16_d16_hi v46, v237 offset:5808
	ds_write_b16 v46, v238 offset:6336
	ds_write_b16_d16_hi v46, v238 offset:6864
	ds_write_b16 v46, v239 offset:7392
	ds_write_b16_d16_hi v46, v239 offset:7920
